# attention top-k loop rewritten: rotating SGPR pairs for compares (no wait-state nops), min3 index search, selected bit from index difference, select instead of exec-masked removal; same algorithm
# speedup vs baseline: 1.0005x; 1.0005x over previous
.LBB0_1218:
	s_add_i32 s12, s33, -2
	v_cmp_ge_i32_e32 vcc, s12, v168
	s_nop 5
	ds_write2st64_b32 v157, v16, v17 offset1:8
	s_nop 0
	ds_write2st64_b32 v157, v0, v1 offset0:128 offset1:136
	ds_write2st64_b32 v157, v18, v19 offset0:16 offset1:24
	ds_write2st64_b32 v157, v2, v3 offset0:144 offset1:152
	ds_write2st64_b32 v157, v20, v21 offset0:32 offset1:40
	ds_write2st64_b32 v157, v4, v5 offset0:160 offset1:168
	ds_write2st64_b32 v157, v22, v23 offset0:48 offset1:56
	ds_write2st64_b32 v157, v6, v7 offset0:176 offset1:184
	ds_write2st64_b32 v157, v24, v25 offset0:64 offset1:72
	ds_write2st64_b32 v157, v8, v9 offset0:192 offset1:200
	ds_write2st64_b32 v157, v26, v27 offset0:80 offset1:88
	ds_write2st64_b32 v157, v10, v11 offset0:208 offset1:216
	ds_write2st64_b32 v157, v28, v29 offset0:96 offset1:104
	ds_write2st64_b32 v157, v12, v13 offset0:224 offset1:232
	ds_write2st64_b32 v157, v30, v31 offset0:112 offset1:120
	ds_write2st64_b32 v157, v14, v15 offset0:240 offset1:248
	s_and_b64 s[14:15], s[50:51], vcc
	v_mov_b32_e32 v0, -1
	v_mov_b32_e32 v1, -1
	s_waitcnt lgkmcnt(0)
	s_barrier
	s_and_saveexec_b64 s[0:1], s[14:15]
	ds_read_b32 v1, v173 offset:36864
	s_or_b64 exec, exec, s[0:1]
	v_cmp_gt_i32_e32 vcc, s12, v168
	s_and_saveexec_b64 s[0:1], vcc
	ds_read_b32 v0, v173 offset:36868
	s_or_b64 exec, exec, s[0:1]
	v_cmp_ge_i32_e32 vcc, s12, v175
	v_mov_b32_e32 v2, -1
	v_mov_b32_e32 v3, -1
	s_and_saveexec_b64 s[0:1], vcc
	ds_read_b32 v3, v173 offset:36872
	s_or_b64 exec, exec, s[0:1]
	v_cmp_ge_i32_e32 vcc, s12, v178
	s_and_saveexec_b64 s[0:1], vcc
	ds_read_b32 v2, v173 offset:36876
	s_or_b64 exec, exec, s[0:1]
	v_cmp_ge_i32_e32 vcc, s12, v188
	v_mov_b32_e32 v4, -1
	v_mov_b32_e32 v5, -1
	s_and_saveexec_b64 s[0:1], vcc
	ds_read_b32 v5, v173 offset:36880
	s_or_b64 exec, exec, s[0:1]
	v_cmp_ge_i32_e32 vcc, s12, v189
	s_and_saveexec_b64 s[0:1], vcc
	ds_read_b32 v4, v173 offset:36884
	s_or_b64 exec, exec, s[0:1]
	v_cmp_ge_i32_e32 vcc, s12, v190
	v_mov_b32_e32 v6, -1
	v_mov_b32_e32 v7, -1
	s_and_saveexec_b64 s[0:1], vcc
	ds_read_b32 v7, v173 offset:36888
	s_or_b64 exec, exec, s[0:1]
	v_cmp_ge_i32_e32 vcc, s12, v191
	s_and_saveexec_b64 s[0:1], vcc
	ds_read_b32 v6, v173 offset:36892
	s_or_b64 exec, exec, s[0:1]
	v_cmp_ge_i32_e32 vcc, s12, v192
	v_mov_b32_e32 v8, -1
	v_mov_b32_e32 v9, -1
	s_and_saveexec_b64 s[0:1], vcc
	ds_read_b32 v9, v173 offset:36896
	s_or_b64 exec, exec, s[0:1]
	v_cmp_ge_i32_e32 vcc, s12, v193
	s_and_saveexec_b64 s[0:1], vcc
	ds_read_b32 v8, v173 offset:36900
	s_or_b64 exec, exec, s[0:1]
	v_cmp_ge_i32_e32 vcc, s12, v194
	v_mov_b32_e32 v10, -1
	v_mov_b32_e32 v11, -1
	s_and_saveexec_b64 s[0:1], vcc
	ds_read_b32 v11, v173 offset:36904
	s_or_b64 exec, exec, s[0:1]
	v_cmp_ge_i32_e32 vcc, s12, v195
	s_and_saveexec_b64 s[0:1], vcc
	ds_read_b32 v10, v173 offset:36908
	s_or_b64 exec, exec, s[0:1]
	v_cmp_ge_i32_e32 vcc, s12, v196
	v_mov_b32_e32 v12, -1
	v_mov_b32_e32 v13, -1
	s_and_saveexec_b64 s[0:1], vcc
	ds_read_b32 v13, v173 offset:36912
	s_or_b64 exec, exec, s[0:1]
	v_cmp_ge_i32_e32 vcc, s12, v197
	s_and_saveexec_b64 s[0:1], vcc
	ds_read_b32 v12, v173 offset:36916
	s_or_b64 exec, exec, s[0:1]
	v_cmp_ge_i32_e32 vcc, s12, v198
	v_mov_b32_e32 v14, -1
	v_mov_b32_e32 v15, -1
	s_and_saveexec_b64 s[0:1], vcc
	ds_read_b32 v15, v173 offset:36920
	s_or_b64 exec, exec, s[0:1]
	v_cmp_ge_i32_e32 vcc, s12, v199
	s_and_saveexec_b64 s[0:1], vcc
	ds_read_b32 v14, v173 offset:36924
	s_or_b64 exec, exec, s[0:1]
	s_cmp_eq_u32 s33, 1
	s_cselect_b32 s0, 14, 13
	s_cmp_lg_u32 s33, 0
	s_cselect_b32 s12, s0, 15
	v_mov_b32_e32 v16, 0
	v_mov_b32_e32 v20, 0xff
	s_branch .LBB0_1252
.LBB0_1251:
	s_add_i32 s12, s12, -1
	s_cmp_eq_u32 s12, 0
	s_cbranch_scc1 .LBB0_1254
.LBB0_1252:
	s_waitcnt lgkmcnt(0)
	v_max_i32_e32 v17, v1, v0
	v_max3_i32 v17, v17, v3, v2
	v_max3_i32 v17, v17, v5, v4
	v_max3_i32 v17, v17, v7, v6
	v_max3_i32 v17, v17, v9, v8
	v_max3_i32 v17, v17, v11, v10
	v_max3_i32 v17, v17, v13, v12
	v_max3_i32 v17, v17, v15, v14
	s_nop 1
	v_max_i32_dpp v17, v17, v17 quad_perm:[1,0,3,2] row_mask:0xf bank_mask:0xf bound_ctrl:1
	s_nop 1
	v_max_i32_dpp v17, v17, v17 quad_perm:[2,3,0,1] row_mask:0xf bank_mask:0xf bound_ctrl:1
	s_nop 1
	v_max_i32_dpp v19, v17, v17 row_half_mirror row_mask:0xf bank_mask:0xf bound_ctrl:1
	v_cmp_lt_i32_e32 vcc, -1, v19
	v_cmp_eq_u32_e64 s[0:1], v1, v19
	v_cmp_eq_u32_e64 s[14:15], v0, v19
	v_cmp_eq_u32_e64 s[98:99], v3, v19
	v_cmp_eq_u32_e64 s[100:101], v2, v19
	v_cndmask_b32_e64 v21, v20, v168, s[0:1]
	v_cmp_eq_u32_e64 s[0:1], v5, v19
	v_cndmask_b32_e64 v22, v20, v174, s[14:15]
	v_cmp_eq_u32_e64 s[14:15], v4, v19
	v_min3_i32 v18, v20, v21, v22
	v_cndmask_b32_e64 v23, v20, v175, s[98:99]
	v_cmp_eq_u32_e64 s[98:99], v7, v19
	v_cndmask_b32_e64 v24, v20, v178, s[100:101]
	v_cmp_eq_u32_e64 s[100:101], v6, v19
	v_min3_i32 v18, v18, v23, v24
	v_cndmask_b32_e64 v21, v20, v188, s[0:1]
	v_cmp_eq_u32_e64 s[0:1], v9, v19
	v_cndmask_b32_e64 v22, v20, v189, s[14:15]
	v_cmp_eq_u32_e64 s[14:15], v8, v19
	v_min3_i32 v18, v18, v21, v22
	v_cndmask_b32_e64 v23, v20, v190, s[98:99]
	v_cmp_eq_u32_e64 s[98:99], v11, v19
	v_cndmask_b32_e64 v24, v20, v191, s[100:101]
	v_cmp_eq_u32_e64 s[100:101], v10, v19
	v_min3_i32 v18, v18, v23, v24
	v_cndmask_b32_e64 v21, v20, v192, s[0:1]
	v_cmp_eq_u32_e64 s[0:1], v13, v19
	v_cndmask_b32_e64 v22, v20, v193, s[14:15]
	v_cmp_eq_u32_e64 s[14:15], v12, v19
	v_min3_i32 v18, v18, v21, v22
	v_cndmask_b32_e64 v23, v20, v194, s[98:99]
	v_cmp_eq_u32_e64 s[98:99], v15, v19
	v_cndmask_b32_e64 v24, v20, v195, s[100:101]
	v_cmp_eq_u32_e64 s[100:101], v14, v19
	v_min3_i32 v18, v18, v23, v24
	v_cndmask_b32_e64 v21, v20, v196, s[0:1]
	v_cndmask_b32_e64 v22, v20, v197, s[14:15]
	v_min3_i32 v18, v18, v21, v22
	v_cndmask_b32_e64 v23, v20, v198, s[98:99]
	v_cndmask_b32_e64 v24, v20, v199, s[100:101]
	v_min3_i32 v18, v18, v23, v24
	s_nop 1
	v_min_i32_dpp v18, v18, v18 quad_perm:[1,0,3,2] row_mask:0xf bank_mask:0xf bound_ctrl:1
	s_nop 1
	v_min_i32_dpp v18, v18, v18 quad_perm:[2,3,0,1] row_mask:0xf bank_mask:0xf bound_ctrl:1
	s_nop 1
	v_min_i32_dpp v17, v18, v18 row_half_mirror row_mask:0xf bank_mask:0xf bound_ctrl:1
	v_cndmask_b32_e32 v17, v20, v17, vcc
	v_sub_u32_e32 v18, v17, v168
	v_cmp_gt_u32_e32 vcc, 16, v18
	v_lshlrev_b32_e64 v21, v18, 1
	v_cmp_eq_u32_e64 s[0:1], v168, v17
	v_cmp_eq_u32_e64 s[14:15], v174, v17
	v_cmp_eq_u32_e64 s[98:99], v175, v17
	v_cmp_eq_u32_e64 s[100:101], v178, v17
	v_cndmask_b32_e32 v21, 0, v21, vcc
	v_or_b32_e32 v16, v16, v21
	v_cndmask_b32_e64 v1, v1, -1, s[0:1]
	v_cmp_eq_u32_e64 s[0:1], v188, v17
	v_cndmask_b32_e64 v0, v0, -1, s[14:15]
	v_cmp_eq_u32_e64 s[14:15], v189, v17
	v_cndmask_b32_e64 v3, v3, -1, s[98:99]
	v_cmp_eq_u32_e64 s[98:99], v190, v17
	v_cndmask_b32_e64 v2, v2, -1, s[100:101]
	v_cmp_eq_u32_e64 s[100:101], v191, v17
	v_cndmask_b32_e64 v5, v5, -1, s[0:1]
	v_cmp_eq_u32_e64 s[0:1], v192, v17
	v_cndmask_b32_e64 v4, v4, -1, s[14:15]
	v_cmp_eq_u32_e64 s[14:15], v193, v17
	v_cndmask_b32_e64 v7, v7, -1, s[98:99]
	v_cmp_eq_u32_e64 s[98:99], v194, v17
	v_cndmask_b32_e64 v6, v6, -1, s[100:101]
	v_cmp_eq_u32_e64 s[100:101], v195, v17
	v_cndmask_b32_e64 v9, v9, -1, s[0:1]
	v_cmp_eq_u32_e64 s[0:1], v196, v17
	v_cndmask_b32_e64 v8, v8, -1, s[14:15]
	v_cmp_eq_u32_e64 s[14:15], v197, v17
	v_cndmask_b32_e64 v11, v11, -1, s[98:99]
	v_cmp_eq_u32_e64 s[98:99], v198, v17
	v_cndmask_b32_e64 v10, v10, -1, s[100:101]
	v_cmp_eq_u32_e64 s[100:101], v199, v17
	v_cndmask_b32_e64 v13, v13, -1, s[0:1]
	v_cndmask_b32_e64 v12, v12, -1, s[14:15]
	v_cndmask_b32_e64 v15, v15, -1, s[98:99]
	v_cndmask_b32_e64 v14, v14, -1, s[100:101]
	s_branch .LBB0_1251
